# stack v1 + retention cvt pipeline + tr_matrix gain de-serialisation + attention segment priority + RES sample rows first
# baseline (speedup 1.0000x reference)
.LBB0_825:
	s_andn2_b64 vcc, exec, s[2:3]
	s_cbranch_vccnz .LBB0_889
	v_readlane_b32 s0, v253, 2
	s_mov_b64 s[2:3], 0
	v_mov_b32_e32 v1, v0
	s_mov_b32 s4, s90
	v_readlane_b32 s1, v253, 3
	s_load_dword s7, s[0:1], 0x0
	v_readfirstlane_b32 s5, v1
	s_ashr_i32 s5, s5, 6
	s_lshl_b32 s4, s4, 3
	s_add_i32 s4, s5, s4
	s_waitcnt lgkmcnt(0)
	s_mov_b32 s1, s7
	s_cmp_eq_u32 s1, 0x100
	s_cselect_b32 s32, 1, 0
	s_cmpk_lt_i32 s4, 0x400
	s_cselect_b32 s36, 0x4000, 0
	s_mul_i32 s36, s36, s32
	s_add_i32 s4, s4, s36
	s_mov_b32 s12, 6
	s_cmpk_gt_i32 s4, 0x43ff
	s_cbranch_scc1 .LBB0_835
	v_readlane_b32 s24, v253, 0
	v_readlane_b32 s25, v253, 1
	s_add_u32 s10, s24, s2
	s_addc_u32 s11, s25, s3
	s_ashr_i32 s13, s12, 31
	s_lshl_b32 s8, s1, 3
	s_lshl_b64 s[12:13], s[12:13], 3
	s_add_u32 s12, s96, s12
	s_addc_u32 s13, s97, s13
	s_load_dwordx2 s[12:13], s[12:13], 0x0
	v_readlane_b32 s0, v252, 41
	s_lshl_b32 s14, s0, 11
	s_lshl_b64 s[22:23], s[14:15], 2
	v_and_b32_e32 v1, 63, v1
	s_waitcnt lgkmcnt(0)
	s_add_u32 s12, s12, s22
	s_addc_u32 s13, s13, s23
	v_lshlrev_b32_e32 v2, 5, v1
	v_lshl_add_u64 v[28:29], s[12:13], 0, v[2:3]
	s_mov_b64 s[0:1], 0x1000
	v_lshl_add_u64 v[24:25], v[28:29], 0, s[0:1]
	s_movk_i32 s0, 0x1000
	global_load_dwordx4 v[4:7], v2, s[12:13]
	global_load_dwordx4 v[8:11], v2, s[12:13] offset:16
	global_load_dwordx4 v[12:15], v2, s[12:13] offset:2048
	global_load_dwordx4 v[16:19], v2, s[12:13] offset:2064
	v_add_co_u32_e32 v30, vcc, s0, v28
	s_mov_b64 s[0:1], 0x1800
	s_nop 0
	v_addc_co_u32_e32 v31, vcc, 0, v29, vcc
	v_lshl_add_u64 v[32:33], v[28:29], 0, s[0:1]
	global_load_dwordx4 v[20:23], v[30:31], off
	s_nop 0
	global_load_dwordx4 v[24:27], v[24:25], off offset:16
	s_nop 0
	global_load_dwordx4 v[28:31], v[30:31], off offset:2048
	s_nop 0
	global_load_dwordx4 v[32:35], v[32:33], off offset:16
	v_lshl_add_u64 v[36:37], s[10:11], 0, v[2:3]
	s_mov_b64 s[0:1], 0x41511000
	s_ashr_i32 s5, s4, 31
	s_waitcnt vmcnt(0)
	v_lshl_add_u64 v[100:101], v[36:37], 0, s[0:1]
	s_lshl_b64 s[10:11], s[4:5], 2
	v_readlane_b32 s0, v252, 6
	s_add_u32 s14, s0, s10
	v_readlane_b32 s0, v252, 7
	s_addc_u32 s23, s0, s11
	s_ashr_i32 s9, s8, 31
	s_lshl_b64 s[12:13], s[8:9], 2
	s_lshl_b64 s[10:11], s[4:5], 12
	s_add_u32 s10, s24, s10
	v_lshlrev_b32_e32 v2, 4, v1
	s_addc_u32 s11, s25, s11
	v_cmp_eq_u32_e64 s[38:39], 0, v1
	v_lshl_add_u64 v[102:103], s[10:11], 0, v[2:3]
	s_lshl_b64 s[28:29], s[8:9], 12
	s_branch .LBB0_829
.LBB0_828:
	s_or_b64 exec, exec, s[26:27]
	s_cmp_eq_u32 s32, 0
	s_cbranch_scc1 .Lres1_orig
	s_cmpk_gt_i32 s4, 0x3fff
	s_cbranch_scc0 .Lres1_adv
	s_sub_i32 s4, s4, 0x4000
	s_sub_u32 s14, s14, 0x10000
	s_subb_u32 s23, s23, 0
	s_mov_b32 s36, 0xfc000000
	s_mov_b32 s37, -1
	v_lshl_add_u64 v[102:103], v[102:103], 0, s[36:37]
	s_branch .LBB0_829
.Lres1_adv:
	s_add_i32 s4, s4, s8
	s_add_u32 s14, s14, s12
	s_addc_u32 s23, s23, s13
	s_cmpk_gt_i32 s4, 0x3fff
	v_lshl_add_u64 v[102:103], v[102:103], 0, s[28:29]
	s_cbranch_scc1 .LBB0_835
	s_branch .LBB0_829
.Lres1_orig:
	s_add_i32 s4, s4, s8
	s_add_u32 s14, s14, s12
	s_addc_u32 s23, s23, s13
	s_cmpk_gt_i32 s4, 0x43ff
	v_lshl_add_u64 v[102:103], v[102:103], 0, s[28:29]
	s_cbranch_scc1 .LBB0_835

.LBB0_1151:
	s_andn2_b64 vcc, exec, s[2:3]
	v_readlane_b32 s0, v252, 41
	s_cbranch_vccnz .LBB0_1169
	v_readlane_b32 s0, v253, 2
	s_mov_b64 s[2:3], 0
	v_mov_b32_e32 v1, v0
	s_mov_b32 s4, s90
	v_readlane_b32 s1, v253, 3
	s_load_dword s24, s[0:1], 0x0
	v_readfirstlane_b32 s5, v1
	s_ashr_i32 s5, s5, 6
	s_lshl_b32 s4, s4, 3
	s_add_i32 s8, s5, s4
	s_waitcnt lgkmcnt(0)
	s_mov_b32 s1, s24
	s_cmp_eq_u32 s1, 0x100
	s_cselect_b32 s32, 1, 0
	s_cmpk_lt_i32 s8, 0x400
	s_cselect_b32 s36, 0x4000, 0
	s_mul_i32 s36, s36, s32
	s_add_i32 s8, s8, s36
	s_mov_b32 s4, 8
	s_cmpk_gt_i32 s8, 0x43ff
	s_cbranch_scc1 .LBB0_1268
	v_readlane_b32 s26, v253, 0
	v_readlane_b32 s27, v253, 1
	s_add_u32 s10, s26, s2
	s_addc_u32 s11, s27, s3
	s_ashr_i32 s5, s4, 31
	s_lshl_b32 s42, s1, 3
	s_lshl_b64 s[4:5], s[4:5], 3
	s_add_u32 s4, s96, s4
	s_addc_u32 s5, s97, s5
	s_load_dwordx2 s[4:5], s[4:5], 0x0
	v_readlane_b32 s1, v252, 41
	s_lshl_b32 s14, s1, 11
	s_lshl_b64 s[12:13], s[14:15], 2
	v_and_b32_e32 v1, 63, v1
	s_waitcnt lgkmcnt(0)
	s_add_u32 s4, s4, s12
	v_lshlrev_b32_e32 v2, 5, v1
	s_addc_u32 s5, s5, s13
	s_waitcnt vmcnt(0)
	v_lshl_add_u64 v[4:5], s[4:5], 0, v[2:3]
	s_mov_b64 s[12:13], 0x1800
	s_movk_i32 s0, 0x1000
	v_lshl_add_u64 v[6:7], v[4:5], 0, s[12:13]
	v_add_co_u32_e32 v12, vcc, s0, v4
	s_mov_b64 s[12:13], 0x1000
	s_nop 0
	v_addc_co_u32_e32 v13, vcc, 0, v5, vcc
	v_lshl_add_u64 v[16:17], v[4:5], 0, s[12:13]
	global_load_dwordx4 v[4:7], v[6:7], off offset:16
	s_nop 0
	global_load_dwordx4 v[8:11], v[12:13], off
	s_nop 0
	global_load_dwordx4 v[12:15], v[12:13], off offset:2048
	s_nop 0
	global_load_dwordx4 v[16:19], v[16:17], off offset:16
	s_nop 0
	global_load_dwordx4 v[20:23], v2, s[4:5] offset:2048
	global_load_dwordx4 v[24:27], v2, s[4:5] offset:2064
	global_load_dwordx4 v[28:31], v2, s[4:5]
	global_load_dwordx4 v[32:35], v2, s[4:5] offset:16
	s_cmp_eq_u32 s1, 3
	v_lshl_add_u64 v[38:39], s[10:11], 0, v[2:3]
	s_mov_b64 s[4:5], 0x41511000
	s_cselect_b64 s[44:45], -1, 0
	s_ashr_i32 s9, s8, 31
	v_lshl_add_u64 v[100:101], v[38:39], 0, s[4:5]
	s_lshl_b64 s[4:5], s[8:9], 2
	v_readlane_b32 s0, v252, 6
	s_add_u32 s14, s0, s4
	v_readlane_b32 s0, v252, 7
	s_addc_u32 s23, s0, s5
	s_ashr_i32 s43, s42, 31
	s_lshl_b64 s[4:5], s[42:43], 2
	s_lshl_b64 s[10:11], s[8:9], 12
	s_add_u32 s10, s26, s10
	v_lshlrev_b32_e32 v2, 4, v1
	s_addc_u32 s11, s27, s11
	v_lshl_add_u64 v[102:103], s[10:11], 0, v[2:3]
	s_lshl_b64 s[46:47], s[42:43], 12
	s_lshl_b64 s[10:11], s[8:9], 13
	s_lshl_b64 s[12:13], s[2:3], 2
	s_add_u32 s1, s10, s12
	v_lshlrev_b32_e32 v36, 1, v1
	s_addc_u32 s9, s11, s13
	v_readlane_b32 s10, v252, 3
	v_or_b32_e32 v38, 0x80, v36
	v_or_b32_e32 v40, 0x100, v36
	v_or_b32_e32 v42, 0x180, v36
	v_readlane_b32 s11, v252, 4
	s_add_u32 s7, s10, s1
	v_cmp_eq_u32_e64 s[38:39], 0, v1
	s_addc_u32 s9, s11, s9
	s_lshl_b64 s[48:49], s[42:43], 13
	v_lshlrev_b32_e32 v1, 4, v36
	v_lshlrev_b32_e32 v2, 4, v38
	v_lshlrev_b32_e32 v130, 4, v40
	v_lshlrev_b32_e32 v131, 4, v42
	s_branch .LBB0_1155
.LBB0_1154:
	s_or_b64 exec, exec, s[12:13]
	s_cmp_eq_u32 s32, 0
	s_cbranch_scc1 .Lres2_orig
	s_cmpk_gt_i32 s8, 0x3fff
	s_cbranch_scc0 .Lres2_adv
	s_sub_i32 s8, s8, 0x4000
	s_sub_u32 s14, s14, 0x10000
	s_subb_u32 s23, s23, 0
	s_sub_u32 s7, s7, 0x8000000
	s_subb_u32 s9, s9, 0
	s_mov_b32 s36, 0xfc000000
	s_mov_b32 s37, -1
	v_lshl_add_u64 v[102:103], v[102:103], 0, s[36:37]
	s_branch .LBB0_1155
.Lres2_adv:
	s_add_i32 s8, s8, s42
	s_add_u32 s14, s14, s4
	s_addc_u32 s23, s23, s5
	s_add_u32 s7, s7, s48
	s_addc_u32 s9, s9, s49
	s_cmpk_gt_i32 s8, 0x3fff
	v_lshl_add_u64 v[102:103], v[102:103], 0, s[46:47]
	s_cbranch_scc1 .LBB0_1268
	s_branch .LBB0_1155
.Lres2_orig:
	s_add_i32 s8, s8, s42
	s_add_u32 s14, s14, s4
	s_addc_u32 s23, s23, s5
	s_add_u32 s7, s7, s48
	s_addc_u32 s9, s9, s49
	s_cmpk_gt_i32 s8, 0x43ff
	v_lshl_add_u64 v[102:103], v[102:103], 0, s[46:47]
	s_cbranch_scc1 .LBB0_1268
